# slc tiles fully in the past skip the element mask (row sel folded into bias); window loop accumulators in place; selection key loads bank-conflict free
# speedup vs baseline: 1.0309x; 1.0063x over previous
; #define ATT_LOOP_END(NT, HASCS) } \
;       if (jt_ + 1 < (NT)) { tile_lstore(L + AL_K + (cur_ ^ 1) * TILE_B, L + AL_V + (cur_ ^ 1) * TILE_B, kr_, vr_, tid); if (HASCS && tid < 64) ((LAS float*)(L + AL_CS))[(cur_ ^ 1) * 64 + tid] = csr_; } \
;       __syncthreads(); } }
; DI void fox_unit(const Params& P, lptr L, int u, int tid, int lane, int wid) {
;     ...
;     ATT_LOOP_END(NT, true)
;     float l = rs.l; l += __shfl_xor(l, 32);
;     const float inv = 1.f / fmaxf(l, 1e-30f);
;     store_o_bf16(ATT + (size_t)(b * SEQ + t) * DM + h * 64, o0, o1, inv, hi);
.Lfox_exit:
	s_nop 3
	v_mov_b64_e32 v[34:35], v[2:3]
	v_mov_b64_e32 v[36:37], v[4:5]
	v_mov_b64_e32 v[38:39], v[6:7]
	v_mov_b64_e32 v[40:41], v[8:9]
	v_mov_b64_e32 v[42:43], v[10:11]
	v_mov_b64_e32 v[44:45], v[12:13]
	v_mov_b64_e32 v[46:47], v[14:15]
	v_mov_b64_e32 v[48:49], v[16:17]
	v_mov_b64_e32 v[50:51], v[18:19]
	v_mov_b64_e32 v[52:53], v[20:21]
	v_mov_b64_e32 v[54:55], v[22:23]
	v_mov_b64_e32 v[56:57], v[24:25]
	v_mov_b64_e32 v[58:59], v[26:27]
	v_mov_b64_e32 v[60:61], v[28:29]
	v_mov_b64_e32 v[62:63], v[30:31]
	v_mov_b64_e32 v[64:65], v[32:33]
	s_branch .LBB0_517

; #define LAS __attribute__((address_space(3)))
; DI void cmpwin_unit(const Params& P, lptr L, int u, int tid, int lane, int wid) {
;     ...
;             const LAS float* tp_ = (const LAS float*)(L + AL_TMP) + ((NTC - 1) & 1) * (8 * 17 * 32);
;             for (int e = tid; e < 2 * 17 * 32; e += 512) { const int q32 = e & 31, jl = (e >> 5) % 17, qh = e / (17 * 32);
;                 const float a = (tp_[((qh * 4 + 0) * 17 + jl) * 32 + q32] + tp_[((qh * 4 + 1) * 17 + jl) * 32 + q32]) + (tp_[((qh * 4 + 2) * 17 + jl) * 32 + q32] + tp_[((qh * 4 + 3) * 17 + jl) * 32 + q32]);
;                 psl[((NTC - 1) * 16 + jl) * PSL_P + qh * 32 + q32] += a; }
;             __syncthreads();
;         }
;         float* prow = PART + row * 512 + head * 64;
; #pragma unroll
;         for (int g4 = 0; g4 < 4; ++g4) {
;             *(f32x4*)(prow + 8 * g4 + 4 * hi) = (f32x4){o0[4 * g4] * gc, o0[4 * g4 + 1] * gc, o0[4 * g4 + 2] * gc, o0[4 * g4 + 3] * gc};
;             *(f32x4*)(prow + 32 + 8 * g4 + 4 * hi) = (f32x4){o1[4 * g4] * gc, o1[4 * g4 + 1] * gc, o1[4 * g4 + 2] * gc, o1[4 * g4 + 3] * gc};
;         }
;     }
;     for (int rp_ = 0; rp_ < ((PROBE_SUB & 2) ? 2 : 1); ++rp_)
;     {
;         const int cur = qb;
;         const int nforced = cur == 0 ? 1 : (cur == 1 ? 2 : 3);
;         const int ncand = max(0, cur - 2), K = min(16, cur + 1) - nforced;
;         const unsigned long long lt_mask = (1ull << lane) - 1ull;
;         for (int qq = 0; qq < 8; ++qq) {
;             const int q = wid * 8 + qq; const int tq = qb * 64 + q;
;             unsigned key[4]; bool cand[4], selb[4];
; #pragma unroll
;             for (int ii = 0; ii < 4; ++ii) { const int j = lane + 64 * ii; key[ii] = __float_as_uint(psl[j * PSL_P + q]);
;                 cand[ii] = (j >= 1) && (j <= cur - 2); selb[ii] = (j == 0) || (j == cur) || (j == cur - 1); }
.LBB0_559:
	v_subrev_u32_e32 v37, 17, v35
	v_cmp_gt_u32_e32 vcc, s11, v36
	s_nop 1
	v_cndmask_b32_e32 v37, v37, v35, vcc
	v_cmp_lt_u32_e32 vcc, s76, v36
	v_add_u32_e32 v35, 16, v35
	s_nop 0
	v_cndmask_b32_e32 v38, 0, v212, vcc
	v_add_u32_e32 v38, v37, v38
	v_lshl_add_u32 v39, v38, 7, v34
	ds_read_b32 v38, v39
	ds_read_b32 v40, v39 offset:2176
	ds_read_b32 v41, v39 offset:4352
	ds_read_b32 v39, v39 offset:6528
	v_add_u32_e32 v37, s2, v37
	v_mul_lo_u32 v37, v37, s6
	v_add_u32_e32 v37, 0, v37
	s_waitcnt lgkmcnt(0)
	v_pk_add_f32 v[38:39], v[40:41], v[38:39]
	s_nop 0
	v_add_f32_e32 v38, v38, v39
	v_cndmask_b32_e32 v39, 0, v213, vcc
	v_lshlrev_b32_e32 v40, 2, v122
	v_add3_u32 v37, v37, v39, v40
	ds_read_b32 v39, v37 offset:37888
	v_cmp_lt_u32_e32 vcc, s77, v36
	s_or_b64 s[0:1], vcc, s[0:1]
	s_waitcnt lgkmcnt(0)
	v_add_f32_e32 v38, v39, v38
	ds_write_b32 v37, v38 offset:37888
	v_add_u32_e32 v37, 0x200, v36
	v_mov_b32_e32 v36, v37
	s_andn2_b64 exec, exec, s[0:1]
	s_cbranch_execnz .LBB0_559
	s_or_b64 exec, exec, s[0:1]
	v_add_f32_e32 v34, 1.0, v84
	v_div_scale_f32 v35, s[0:1], v34, v34, 1.0
	v_rcp_f32_e32 v36, v35
	v_div_scale_f32 v37, vcc, 1.0, v34, 1.0
	s_lshl_b32 s60, s51, 2
	v_fma_f32 v38, -v35, v36, 1.0
	v_fmac_f32_e32 v36, v38, v36
	v_mul_f32_e32 v38, v37, v36
	v_fma_f32 v39, -v35, v38, v37
	v_readlane_b32 s0, v250, 0
	v_fmac_f32_e32 v38, v39, v36
	v_readlane_b32 s1, v250, 1
	s_add_u32 s0, s0, s60
	v_fma_f32 v35, -v35, v38, v37
	s_addc_u32 s1, s1, 0
	v_div_fmas_f32 v35, v35, v36, v38
	v_lshlrev_b64 v[36:37], 11, v[0:1]
	s_cmpk_eq_i32 s61, 0xfe
	v_lshl_add_u64 v[36:37], s[0:1], 0, v[36:37]
	s_cselect_b32 s0, -2, -3
	s_cmpk_lg_i32 s61, 0xff
	s_cselect_b32 s33, s0, -1
	s_sub_i32 s1, 0x100, s61
	s_sub_i32 s2, 0xfd, s61
	s_min_u32 s1, s1, 16
	s_max_i32 s0, s2, 0
	s_add_i32 s33, s33, s1
	s_sub_i32 s3, 0xfe, s61
	v_div_fixup_f32 v34, v35, v34, 1.0
	v_lshlrev_b32_e32 v154, 2, v134
	v_mov_b32_e32 v155, v1
	s_cmp_lt_i32 s33, s0
	v_readlane_b32 s0, v250, 23
	v_lshl_add_u64 v[158:159], v[36:37], 0, v[154:155]
	v_pk_mul_f32 v[2:3], v[34:35], v[2:3] op_sel_hi:[0,1]
	v_pk_mul_f32 v[4:5], v[34:35], v[4:5] op_sel_hi:[0,1]
	v_cmp_ge_i32_e32 vcc, s2, v192
	v_readlane_b32 s1, v250, 24
	s_waitcnt lgkmcnt(0)
	s_barrier
	global_store_dwordx4 v[158:159], v[2:5], off
	s_cselect_b64 s[28:29], -1, 0
	s_and_b64 s[70:71], s[0:1], vcc
	v_pk_mul_f32 v[2:3], v[34:35], v[18:19] op_sel_hi:[0,1]
	v_pk_mul_f32 v[4:5], v[34:35], v[20:21] op_sel_hi:[0,1]
	v_cmp_eq_u32_e32 vcc, s41, v192
	global_store_dwordx4 v[158:159], v[2:5], off offset:128
	s_or_b64 s[0:1], s[12:13], vcc
	v_cmp_eq_u32_e32 vcc, s3, v192
	v_pk_mul_f32 v[2:3], v[34:35], v[6:7] op_sel_hi:[0,1]
	v_pk_mul_f32 v[4:5], v[34:35], v[8:9] op_sel_hi:[0,1]
	global_store_dwordx4 v[158:159], v[2:5], off offset:32
	s_or_b64 s[78:79], s[0:1], vcc
	v_cmp_eq_u32_e32 vcc, s41, v175
	v_pk_mul_f32 v[2:3], v[34:35], v[22:23] op_sel_hi:[0,1]
	v_pk_mul_f32 v[4:5], v[34:35], v[24:25] op_sel_hi:[0,1]
	v_cmp_eq_u32_e64 s[0:1], s3, v175
	global_store_dwordx4 v[158:159], v[2:5], off offset:160
	s_or_b64 s[30:31], vcc, s[0:1]
	v_cmp_eq_u32_e32 vcc, s41, v176
	v_pk_mul_f32 v[2:3], v[34:35], v[10:11] op_sel_hi:[0,1]
	v_pk_mul_f32 v[4:5], v[34:35], v[12:13] op_sel_hi:[0,1]
	v_cmp_eq_u32_e64 s[0:1], s3, v176
	global_store_dwordx4 v[158:159], v[2:5], off offset:64
	s_or_b64 s[64:65], vcc, s[0:1]
	v_cmp_eq_u32_e32 vcc, s41, v178
	v_pk_mul_f32 v[2:3], v[34:35], v[26:27] op_sel_hi:[0,1]
	v_pk_mul_f32 v[4:5], v[34:35], v[28:29] op_sel_hi:[0,1]
	v_cmp_eq_u32_e64 s[0:1], s3, v178
	global_store_dwordx4 v[158:159], v[2:5], off offset:192
	v_cmp_ge_i32_e64 s[22:23], s2, v175
	v_cmp_ge_i32_e64 s[24:25], s2, v176
	v_pk_mul_f32 v[2:3], v[34:35], v[14:15] op_sel_hi:[0,1]
	v_pk_mul_f32 v[4:5], v[34:35], v[16:17] op_sel_hi:[0,1]
	v_cmp_ge_i32_e64 s[26:27], s2, v178
	s_or_b64 s[74:75], vcc, s[0:1]
	global_store_dwordx4 v[158:159], v[2:5], off offset:96
	s_mov_b32 s82, 0
	s_mov_b32 s39, s41
	v_pk_mul_f32 v[2:3], v[34:35], v[30:31] op_sel_hi:[0,1]
	v_pk_mul_f32 v[4:5], v[34:35], v[32:33] op_sel_hi:[0,1]
	s_or_b64 s[68:69], s[78:79], s[70:71]
	s_or_b64 s[2:3], s[30:31], s[22:23]
	s_or_b64 s[42:43], s[64:65], s[24:25]
	s_or_b64 s[58:59], s[74:75], s[26:27]
	global_store_dwordx4 v[158:159], v[2:5], off offset:224
	v_and_b32_e32 v12, 7, v192
	v_lshrrev_b32_e32 v13, 3, v192
	v_add_u32_e32 v13, s93, v13
	v_lshlrev_b32_e32 v14, 5, v12
	v_mov_b32_e32 v0, 0x410
	v_mul_u32_u24_e32 v15, 0x2080, v12
	v_lshl_add_u32 v15, v13, 2, v15
	v_add_u32_e32 v26, 0, v12
	v_and_b32_e32 v26, 7, v26
	v_mad_u32_u24 v26, v26, v0, v15
	v_add_u32_e32 v27, 1, v12
	v_and_b32_e32 v27, 7, v27
	v_mad_u32_u24 v27, v27, v0, v15
	v_add_u32_e32 v28, 2, v12
	v_and_b32_e32 v28, 7, v28
	v_mad_u32_u24 v28, v28, v0, v15
	v_add_u32_e32 v29, 3, v12
	v_and_b32_e32 v29, 7, v29
	v_mad_u32_u24 v29, v29, v0, v15
	v_add_u32_e32 v30, 4, v12
	v_and_b32_e32 v30, 7, v30
	v_mad_u32_u24 v30, v30, v0, v15
	v_add_u32_e32 v31, 5, v12
	v_and_b32_e32 v31, 7, v31
	v_mad_u32_u24 v31, v31, v0, v15
	v_add_u32_e32 v32, 6, v12
	v_and_b32_e32 v32, 7, v32
	v_mad_u32_u24 v32, v32, v0, v15
	v_add_u32_e32 v33, 7, v12
	v_and_b32_e32 v33, 7, v33
	v_mad_u32_u24 v33, v33, v0, v15
	ds_read_b32 v228, v26 offset:37888
	ds_read_b32 v229, v26 offset:38148
	ds_read_b32 v230, v26 offset:38408
	ds_read_b32 v231, v26 offset:38668
	ds_read_b32 v232, v27 offset:37888
	ds_read_b32 v233, v27 offset:38148
	ds_read_b32 v234, v27 offset:38408
	ds_read_b32 v235, v27 offset:38668
	ds_read_b32 v236, v28 offset:37888
	ds_read_b32 v237, v28 offset:38148
	ds_read_b32 v238, v28 offset:38408
	ds_read_b32 v239, v28 offset:38668
	ds_read_b32 v240, v29 offset:37888
; DI void cmpwin_unit(const Params& P, lptr L, int u, int tid, int lane, int wid) {
;     ...
;             for (int ii = 0; ii < 4; ++ii) { const int j = lane + 64 * ii; key[ii] = __float_as_uint(psl[j * PSL_P + q]);
;                 cand[ii] = (j >= 1) && (j <= cur - 2); selb[ii] = (j == 0) || (j == cur) || (j == cur - 1); }
;             if (K >= ncand) {
; #pragma unroll
;                 for (int ii = 0; ii < 4; ++ii) selb[ii] = selb[ii] || cand[ii];
;             } else {
;                 unsigned tau = 0u;
;     ...
;                     const unsigned trial = tau | (1u << bit);
;                     int cnt = 0;
; #pragma unroll
;                     for (int ii = 0; ii < 4; ++ii) cnt += __popcll(__ballot(cand[ii] && key[ii] >= trial));
;                     if (cnt == K) { tau = trial - 1u; break; }
;                     if (cnt > K) tau = trial;
;                 }
	ds_read_b32 v241, v29 offset:38148
	ds_read_b32 v242, v29 offset:38408
	ds_read_b32 v243, v29 offset:38668
	ds_read_b32 v244, v30 offset:37888
	ds_read_b32 v245, v30 offset:38148
	ds_read_b32 v246, v30 offset:38408
	ds_read_b32 v247, v30 offset:38668
	ds_read_b32 v248, v31 offset:37888
	ds_read_b32 v17, v31 offset:38148
	ds_read_b32 v252, v31 offset:38408
	ds_read_b32 v253, v31 offset:38668
	ds_read_b32 v254, v32 offset:37888
	ds_read_b32 v255, v32 offset:38148
	ds_read_b32 v6, v32 offset:38408
	ds_read_b32 v7, v32 offset:38668
	ds_read_b32 v8, v33 offset:37888
	ds_read_b32 v9, v33 offset:38148
	ds_read_b32 v10, v33 offset:38408
	ds_read_b32 v11, v33 offset:38668
	v_lshlrev_b32_e32 v2, 2, v12
	v_sub_u32_e32 v3, 32, v2
	v_and_b32_e32 v3, 31, v3
	s_add_i32 s100, s39, -1
	s_lshl_b32 s101, s93, 5
	s_add_i32 s101, s101, 0x19904
	v_mov_b32_e32 v18, 1
	v_mov_b32_e32 v19, 0
	v_sub_u32_e32 v16, s100, v14
	v_max_i32_e32 v16, 0, v16
	v_min_i32_e32 v16, 32, v16
	v_lshlrev_b64 v[20:21], v16, v[18:19]
	v_add_u32_e32 v22, -1, v20
	v_cmp_eq_u32_e32 vcc, 0, v12
	s_nop 1
	v_cndmask_b32_e64 v23, 0, 1, vcc
	v_xor_b32_e32 v24, -1, v23
	v_and_b32_e32 v22, v22, v24
	v_sub_u32_e32 v25, s39, v14
	v_cmp_gt_u32_e32 vcc, 32, v25
	v_lshlrev_b32_e64 v24, v25, 1
	s_nop 0
	v_cndmask_b32_e32 v24, 0, v24, vcc
	v_or_b32_e32 v23, v23, v24
	v_sub_u32_e32 v25, s100, v14
	v_cmp_gt_u32_e32 vcc, 32, v25
	v_lshlrev_b32_e64 v24, v25, 1
	s_nop 0
	v_cndmask_b32_e32 v24, 0, v24, vcc
	v_or_b32_e32 v23, v23, v24
	v_or_b32_e32 v32, v23, v22
	s_and_b64 vcc, exec, s[28:29]
	s_cbranch_vccz .Lsel_store
	s_waitcnt lgkmcnt(0)
	v_alignbit_b32 v4, v22, v22, v2
	v_bfe_i32 v24, v4, 0, 1
	v_and_b32_e32 v228, v228, v24
	v_bfe_i32 v25, v4, 1, 1
	v_and_b32_e32 v229, v229, v25
	v_bfe_i32 v24, v4, 2, 1
	v_and_b32_e32 v230, v230, v24
	v_bfe_i32 v25, v4, 3, 1
	v_and_b32_e32 v231, v231, v25
	v_bfe_i32 v24, v4, 4, 1
	v_and_b32_e32 v232, v232, v24
	v_bfe_i32 v25, v4, 5, 1
	v_and_b32_e32 v233, v233, v25
	v_bfe_i32 v24, v4, 6, 1
	v_and_b32_e32 v234, v234, v24
	v_bfe_i32 v25, v4, 7, 1
	v_and_b32_e32 v235, v235, v25
	v_bfe_i32 v24, v4, 8, 1
	v_and_b32_e32 v236, v236, v24
	v_bfe_i32 v25, v4, 9, 1
	v_and_b32_e32 v237, v237, v25
	v_bfe_i32 v24, v4, 10, 1
	v_and_b32_e32 v238, v238, v24
	v_bfe_i32 v25, v4, 11, 1
	v_and_b32_e32 v239, v239, v25
	v_bfe_i32 v24, v4, 12, 1
	v_and_b32_e32 v240, v240, v24
	v_bfe_i32 v25, v4, 13, 1
	v_and_b32_e32 v241, v241, v25
	v_bfe_i32 v24, v4, 14, 1
	v_and_b32_e32 v242, v242, v24
	v_bfe_i32 v25, v4, 15, 1
	v_and_b32_e32 v243, v243, v25
	v_bfe_i32 v24, v4, 16, 1
	v_and_b32_e32 v244, v244, v24
	v_bfe_i32 v25, v4, 17, 1
	v_and_b32_e32 v245, v245, v25
	v_bfe_i32 v24, v4, 18, 1
	v_and_b32_e32 v246, v246, v24
	v_bfe_i32 v25, v4, 19, 1
	v_and_b32_e32 v247, v247, v25
	v_bfe_i32 v24, v4, 20, 1
	v_and_b32_e32 v248, v248, v24
	v_bfe_i32 v25, v4, 21, 1
	v_and_b32_e32 v17, v17, v25
	v_bfe_i32 v24, v4, 22, 1
	v_and_b32_e32 v252, v252, v24
	v_bfe_i32 v25, v4, 23, 1
	v_and_b32_e32 v253, v253, v25
	v_bfe_i32 v24, v4, 24, 1
	v_and_b32_e32 v254, v254, v24
	v_bfe_i32 v25, v4, 25, 1
	v_and_b32_e32 v255, v255, v25
	v_bfe_i32 v24, v4, 26, 1
	v_and_b32_e32 v6, v6, v24
	v_bfe_i32 v25, v4, 27, 1
	v_and_b32_e32 v7, v7, v25
	v_bfe_i32 v24, v4, 28, 1
	v_and_b32_e32 v8, v8, v24
	v_bfe_i32 v25, v4, 29, 1
	v_and_b32_e32 v9, v9, v25
	v_bfe_i32 v24, v4, 30, 1
	v_and_b32_e32 v10, v10, v24
	v_bfe_i32 v25, v4, 31, 1
	v_and_b32_e32 v11, v11, v25
	v_mov_b32_e32 v26, 0
	s_mov_b64 s[52:53], 0
	s_mov_b32 s98, 30
.Lsel_loop:
	s_lshl_b32 s99, 1, s98
	v_or_b32_e32 v27, s99, v26
	v_mov_b32_e32 v28, 0
	v_mov_b32_e32 v29, 0
	v_cmp_ge_u32_e64 s[22:23], v228, v27
	v_cmp_ge_u32_e64 s[24:25], v229, v27
	v_cmp_ge_u32_e64 s[26:27], v230, v27
	v_addc_co_u32_e64 v28, vcc, v28, 0, s[22:23]
	v_cmp_ge_u32_e64 s[22:23], v231, v27
	v_addc_co_u32_e64 v29, vcc, v29, 0, s[24:25]
	v_cmp_ge_u32_e64 s[24:25], v232, v27
	v_addc_co_u32_e64 v28, vcc, v28, 0, s[26:27]
	v_cmp_ge_u32_e64 s[26:27], v233, v27
	v_addc_co_u32_e64 v29, vcc, v29, 0, s[22:23]
	v_cmp_ge_u32_e64 s[22:23], v234, v27
	v_addc_co_u32_e64 v28, vcc, v28, 0, s[24:25]
	v_cmp_ge_u32_e64 s[24:25], v235, v27
	v_addc_co_u32_e64 v29, vcc, v29, 0, s[26:27]
	v_cmp_ge_u32_e64 s[26:27], v236, v27
	v_addc_co_u32_e64 v28, vcc, v28, 0, s[22:23]
	v_cmp_ge_u32_e64 s[22:23], v237, v27
	v_addc_co_u32_e64 v29, vcc, v29, 0, s[24:25]
	v_cmp_ge_u32_e64 s[24:25], v238, v27
	v_addc_co_u32_e64 v28, vcc, v28, 0, s[26:27]
	v_cmp_ge_u32_e64 s[26:27], v239, v27
	v_addc_co_u32_e64 v29, vcc, v29, 0, s[22:23]
	v_cmp_ge_u32_e64 s[22:23], v240, v27
	v_addc_co_u32_e64 v28, vcc, v28, 0, s[24:25]
	v_cmp_ge_u32_e64 s[24:25], v241, v27
	v_addc_co_u32_e64 v29, vcc, v29, 0, s[26:27]
	v_cmp_ge_u32_e64 s[26:27], v242, v27
	v_addc_co_u32_e64 v28, vcc, v28, 0, s[22:23]
	v_cmp_ge_u32_e64 s[22:23], v243, v27
	v_addc_co_u32_e64 v29, vcc, v29, 0, s[24:25]
	v_cmp_ge_u32_e64 s[24:25], v244, v27
	v_addc_co_u32_e64 v28, vcc, v28, 0, s[26:27]
	v_cmp_ge_u32_e64 s[26:27], v245, v27
	v_addc_co_u32_e64 v29, vcc, v29, 0, s[22:23]
	v_cmp_ge_u32_e64 s[22:23], v246, v27
	v_addc_co_u32_e64 v28, vcc, v28, 0, s[24:25]
	v_cmp_ge_u32_e64 s[24:25], v247, v27
	v_addc_co_u32_e64 v29, vcc, v29, 0, s[26:27]
	v_cmp_ge_u32_e64 s[26:27], v248, v27
	v_addc_co_u32_e64 v28, vcc, v28, 0, s[22:23]
	v_cmp_ge_u32_e64 s[22:23], v17, v27
	v_addc_co_u32_e64 v29, vcc, v29, 0, s[24:25]
	v_cmp_ge_u32_e64 s[24:25], v252, v27
	v_addc_co_u32_e64 v28, vcc, v28, 0, s[26:27]
	v_cmp_ge_u32_e64 s[26:27], v253, v27
	v_addc_co_u32_e64 v29, vcc, v29, 0, s[22:23]
	v_cmp_ge_u32_e64 s[22:23], v254, v27
	v_addc_co_u32_e64 v28, vcc, v28, 0, s[24:25]
	v_cmp_ge_u32_e64 s[24:25], v255, v27
	v_addc_co_u32_e64 v29, vcc, v29, 0, s[26:27]
	v_cmp_ge_u32_e64 s[26:27], v6, v27
	v_addc_co_u32_e64 v28, vcc, v28, 0, s[22:23]
	v_cmp_ge_u32_e64 s[22:23], v7, v27
	v_addc_co_u32_e64 v29, vcc, v29, 0, s[24:25]
	v_cmp_ge_u32_e64 s[24:25], v8, v27
	v_addc_co_u32_e64 v28, vcc, v28, 0, s[26:27]
	v_cmp_ge_u32_e64 s[26:27], v9, v27
	v_addc_co_u32_e64 v29, vcc, v29, 0, s[22:23]
	v_cmp_ge_u32_e64 s[22:23], v10, v27
	v_addc_co_u32_e64 v28, vcc, v28, 0, s[24:25]
	v_cmp_ge_u32_e64 s[24:25], v11, v27
	v_addc_co_u32_e64 v29, vcc, v29, 0, s[26:27]
	v_addc_co_u32_e64 v28, vcc, v28, 0, s[22:23]
	v_addc_co_u32_e64 v29, vcc, v29, 0, s[24:25]
	v_add_u32_e32 v30, v28, v29
	s_nop 1
	v_add_u32_dpp v24, v30, v30 quad_perm:[1,0,3,2] row_mask:0xf bank_mask:0xf
	s_nop 1
	v_add_u32_dpp v25, v24, v24 quad_perm:[2,3,0,1] row_mask:0xf bank_mask:0xf
	s_nop 1
	v_add_u32_dpp v30, v25, v25 row_half_mirror row_mask:0xf bank_mask:0xf
	v_add_u32_e32 v31, -1, v27
	v_cmp_lt_u32_e64 s[24:25], s33, v30
	v_cmp_eq_u32_e64 s[26:27], s33, v30
	s_andn2_b64 s[24:25], s[24:25], s[52:53]
	s_andn2_b64 s[26:27], s[26:27], s[52:53]
	s_or_b64 s[52:53], s[52:53], s[26:27]
	v_cndmask_b32_e64 v26, v26, v27, s[24:25]
	v_cndmask_b32_e64 v26, v26, v31, s[26:27]
	s_add_i32 s98, s98, -1
	s_cmp_lt_i32 s98, 0
	s_cbranch_scc1 .Lsel_bisected
	s_cmp_eq_u64 s[52:53], -1
	s_cbranch_scc0 .Lsel_loop
; DI void cmpwin_unit(const Params& P, lptr L, int u, int tid, int lane, int wid) {
;     ...
;                 int cgt = 0;
; #pragma unroll
;                 for (int ii = 0; ii < 4; ++ii) cgt += __popcll(__ballot(cand[ii] && key[ii] > tau));
;                 int need = K - cgt;
.Lsel_bisected:
	v_mov_b32_e32 v32, 0
	v_mov_b32_e32 v33, 0
	v_cmp_gt_u32_e64 s[22:23], v11, v26
	v_cmp_gt_u32_e64 s[24:25], v10, v26
	v_cmp_gt_u32_e64 s[26:27], v9, v26
	v_addc_co_u32_e64 v32, vcc, v32, v32, s[22:23]
	v_cmp_gt_u32_e64 s[22:23], v8, v26
	v_addc_co_u32_e64 v32, vcc, v32, v32, s[24:25]
	v_cmp_gt_u32_e64 s[24:25], v7, v26
	v_addc_co_u32_e64 v32, vcc, v32, v32, s[26:27]
	v_cmp_gt_u32_e64 s[26:27], v6, v26
	v_addc_co_u32_e64 v32, vcc, v32, v32, s[22:23]
	v_cmp_gt_u32_e64 s[22:23], v255, v26
	v_addc_co_u32_e64 v32, vcc, v32, v32, s[24:25]
	v_cmp_gt_u32_e64 s[24:25], v254, v26
	v_addc_co_u32_e64 v32, vcc, v32, v32, s[26:27]
	v_cmp_gt_u32_e64 s[26:27], v253, v26
	v_addc_co_u32_e64 v32, vcc, v32, v32, s[22:23]
	v_cmp_gt_u32_e64 s[22:23], v252, v26
	v_addc_co_u32_e64 v32, vcc, v32, v32, s[24:25]
	v_cmp_gt_u32_e64 s[24:25], v17, v26
	v_addc_co_u32_e64 v32, vcc, v32, v32, s[26:27]
	v_cmp_gt_u32_e64 s[26:27], v248, v26
	v_addc_co_u32_e64 v32, vcc, v32, v32, s[22:23]
	v_cmp_gt_u32_e64 s[22:23], v247, v26
	v_addc_co_u32_e64 v32, vcc, v32, v32, s[24:25]
	v_cmp_gt_u32_e64 s[24:25], v246, v26
	v_addc_co_u32_e64 v32, vcc, v32, v32, s[26:27]
	v_cmp_gt_u32_e64 s[26:27], v245, v26
	v_addc_co_u32_e64 v32, vcc, v32, v32, s[22:23]
	v_cmp_gt_u32_e64 s[22:23], v244, v26
	v_addc_co_u32_e64 v32, vcc, v32, v32, s[24:25]
	v_cmp_gt_u32_e64 s[24:25], v243, v26
	v_addc_co_u32_e64 v32, vcc, v32, v32, s[26:27]
	v_cmp_gt_u32_e64 s[26:27], v242, v26
	v_addc_co_u32_e64 v32, vcc, v32, v32, s[22:23]
	v_cmp_gt_u32_e64 s[22:23], v241, v26
	v_addc_co_u32_e64 v32, vcc, v32, v32, s[24:25]
	v_cmp_gt_u32_e64 s[24:25], v240, v26
	v_addc_co_u32_e64 v32, vcc, v32, v32, s[26:27]
	v_cmp_gt_u32_e64 s[26:27], v239, v26
	v_addc_co_u32_e64 v32, vcc, v32, v32, s[22:23]
	v_cmp_gt_u32_e64 s[22:23], v238, v26
	v_addc_co_u32_e64 v32, vcc, v32, v32, s[24:25]
	v_cmp_gt_u32_e64 s[24:25], v237, v26
	v_addc_co_u32_e64 v32, vcc, v32, v32, s[26:27]
	v_cmp_gt_u32_e64 s[26:27], v236, v26
	v_addc_co_u32_e64 v32, vcc, v32, v32, s[22:23]
	v_cmp_gt_u32_e64 s[22:23], v235, v26
	v_addc_co_u32_e64 v32, vcc, v32, v32, s[24:25]
	v_cmp_gt_u32_e64 s[24:25], v234, v26
	v_addc_co_u32_e64 v32, vcc, v32, v32, s[26:27]
	v_cmp_gt_u32_e64 s[26:27], v233, v26
	v_addc_co_u32_e64 v32, vcc, v32, v32, s[22:23]
	v_cmp_gt_u32_e64 s[22:23], v232, v26
	v_addc_co_u32_e64 v32, vcc, v32, v32, s[24:25]
	v_cmp_gt_u32_e64 s[24:25], v231, v26
	v_addc_co_u32_e64 v32, vcc, v32, v32, s[26:27]
	v_cmp_gt_u32_e64 s[26:27], v230, v26
	v_addc_co_u32_e64 v32, vcc, v32, v32, s[22:23]
	v_cmp_gt_u32_e64 s[22:23], v229, v26
	v_addc_co_u32_e64 v32, vcc, v32, v32, s[24:25]
	v_cmp_gt_u32_e64 s[24:25], v228, v26
	v_addc_co_u32_e64 v32, vcc, v32, v32, s[26:27]
	v_addc_co_u32_e64 v32, vcc, v32, v32, s[22:23]
	v_addc_co_u32_e64 v32, vcc, v32, v32, s[24:25]
	v_cmp_eq_u32_e64 s[22:23], v11, v26
	v_cmp_eq_u32_e64 s[24:25], v10, v26
	v_cmp_eq_u32_e64 s[26:27], v9, v26
	v_addc_co_u32_e64 v33, vcc, v33, v33, s[22:23]
	v_cmp_eq_u32_e64 s[22:23], v8, v26
	v_addc_co_u32_e64 v33, vcc, v33, v33, s[24:25]
	v_cmp_eq_u32_e64 s[24:25], v7, v26
	v_addc_co_u32_e64 v33, vcc, v33, v33, s[26:27]
	v_cmp_eq_u32_e64 s[26:27], v6, v26
	v_addc_co_u32_e64 v33, vcc, v33, v33, s[22:23]
	v_cmp_eq_u32_e64 s[22:23], v255, v26
	v_addc_co_u32_e64 v33, vcc, v33, v33, s[24:25]
	v_cmp_eq_u32_e64 s[24:25], v254, v26
	v_addc_co_u32_e64 v33, vcc, v33, v33, s[26:27]
	v_cmp_eq_u32_e64 s[26:27], v253, v26
	v_addc_co_u32_e64 v33, vcc, v33, v33, s[22:23]
	v_cmp_eq_u32_e64 s[22:23], v252, v26
	v_addc_co_u32_e64 v33, vcc, v33, v33, s[24:25]
	v_cmp_eq_u32_e64 s[24:25], v17, v26
	v_addc_co_u32_e64 v33, vcc, v33, v33, s[26:27]
	v_cmp_eq_u32_e64 s[26:27], v248, v26
	v_addc_co_u32_e64 v33, vcc, v33, v33, s[22:23]
	v_cmp_eq_u32_e64 s[22:23], v247, v26
	v_addc_co_u32_e64 v33, vcc, v33, v33, s[24:25]
	v_cmp_eq_u32_e64 s[24:25], v246, v26
	v_addc_co_u32_e64 v33, vcc, v33, v33, s[26:27]
	v_cmp_eq_u32_e64 s[26:27], v245, v26
	v_addc_co_u32_e64 v33, vcc, v33, v33, s[22:23]
	v_cmp_eq_u32_e64 s[22:23], v244, v26
	v_addc_co_u32_e64 v33, vcc, v33, v33, s[24:25]
	v_cmp_eq_u32_e64 s[24:25], v243, v26
	v_addc_co_u32_e64 v33, vcc, v33, v33, s[26:27]
	v_cmp_eq_u32_e64 s[26:27], v242, v26
	v_addc_co_u32_e64 v33, vcc, v33, v33, s[22:23]
	v_cmp_eq_u32_e64 s[22:23], v241, v26
	v_addc_co_u32_e64 v33, vcc, v33, v33, s[24:25]
	v_cmp_eq_u32_e64 s[24:25], v240, v26
	v_addc_co_u32_e64 v33, vcc, v33, v33, s[26:27]
	v_cmp_eq_u32_e64 s[26:27], v239, v26
	v_addc_co_u32_e64 v33, vcc, v33, v33, s[22:23]
	v_cmp_eq_u32_e64 s[22:23], v238, v26
	v_addc_co_u32_e64 v33, vcc, v33, v33, s[24:25]
	v_cmp_eq_u32_e64 s[24:25], v237, v26
	v_addc_co_u32_e64 v33, vcc, v33, v33, s[26:27]
	v_cmp_eq_u32_e64 s[26:27], v236, v26
	v_addc_co_u32_e64 v33, vcc, v33, v33, s[22:23]
	v_cmp_eq_u32_e64 s[22:23], v235, v26
	v_addc_co_u32_e64 v33, vcc, v33, v33, s[24:25]
	v_cmp_eq_u32_e64 s[24:25], v234, v26
	v_addc_co_u32_e64 v33, vcc, v33, v33, s[26:27]
	v_cmp_eq_u32_e64 s[26:27], v233, v26
	v_addc_co_u32_e64 v33, vcc, v33, v33, s[22:23]
	v_cmp_eq_u32_e64 s[22:23], v232, v26
	v_addc_co_u32_e64 v33, vcc, v33, v33, s[24:25]
	v_cmp_eq_u32_e64 s[24:25], v231, v26
	v_addc_co_u32_e64 v33, vcc, v33, v33, s[26:27]
	v_cmp_eq_u32_e64 s[26:27], v230, v26
	v_addc_co_u32_e64 v33, vcc, v33, v33, s[22:23]
	v_cmp_eq_u32_e64 s[22:23], v229, v26
	v_addc_co_u32_e64 v33, vcc, v33, v33, s[24:25]
	v_cmp_eq_u32_e64 s[24:25], v228, v26
	v_addc_co_u32_e64 v33, vcc, v33, v33, s[26:27]
	v_addc_co_u32_e64 v33, vcc, v33, v33, s[22:23]
	v_addc_co_u32_e64 v33, vcc, v33, v33, s[24:25]
	v_alignbit_b32 v32, v32, v32, v3
	v_alignbit_b32 v33, v33, v33, v3
	v_and_b32_e32 v33, v33, v22
	v_bcnt_u32_b32 v30, v32, 0
	s_nop 1
	v_add_u32_dpp v24, v30, v30 quad_perm:[1,0,3,2] row_mask:0xf bank_mask:0xf
	s_nop 1
	v_add_u32_dpp v25, v24, v24 quad_perm:[2,3,0,1] row_mask:0xf bank_mask:0xf
	s_nop 1
	v_add_u32_dpp v30, v25, v25 row_half_mirror row_mask:0xf bank_mask:0xf
	v_sub_u32_e32 v16, s33, v30
	v_cmp_lt_i32_e32 vcc, 0, v16
	s_cbranch_vccz .Lsel_merge
; DI void cmpwin_unit(const Params& P, lptr L, int u, int tid, int lane, int wid) {
;     ...
;                 int need = K - cgt;
; #pragma unroll
;                 for (int ii = 0; ii < 4; ++ii) {
;                     const bool eq = cand[ii] && key[ii] == tau;
;                     const unsigned long long bal = __ballot(eq);
;                     const int rank = __popcll(bal & lt_mask);
;                     selb[ii] = selb[ii] || (cand[ii] && key[ii] > tau) || (eq && rank < need);
;                     need = max(0, need - (int)__popcll(bal));
;                 }
	v_bcnt_u32_b32 v0, v33, 0
	v_cmp_le_u32_e64 s[22:23], 1, v12
	v_cmp_le_u32_e64 s[24:25], 2, v12
	v_cmp_le_u32_e64 s[26:27], 4, v12
	v_mov_b32_e32 v24, 0
	s_nop 0
	v_mov_b32_dpp v24, v0 row_shr:1 row_mask:0xf bank_mask:0xf bound_ctrl:0
	s_nop 1
	v_cndmask_b32_e64 v24, 0, v24, s[22:23]
	v_add_u32_e32 v7, v0, v24
	v_mov_b32_e32 v24, 0
	s_nop 0
	v_mov_b32_dpp v24, v7 row_shr:2 row_mask:0xf bank_mask:0xf bound_ctrl:0
	s_nop 1
	v_cndmask_b32_e64 v24, 0, v24, s[24:25]
	v_add_u32_e32 v7, v7, v24
	v_mov_b32_e32 v24, 0
	s_nop 0
	v_mov_b32_dpp v24, v7 row_shr:4 row_mask:0xf bank_mask:0xf bound_ctrl:0
	s_nop 1
	v_cndmask_b32_e64 v24, 0, v24, s[26:27]
	v_add_u32_e32 v7, v7, v24
	v_sub_u32_e32 v7, v7, v0
	v_sub_u32_e32 v7, v16, v7
	v_max_i32_e32 v7, 0, v7
	v_min_i32_e32 v7, v7, v0
	v_mov_b32_e32 v25, v33
	v_cmp_lt_u32_e32 vcc, 0, v7
	v_add_u32_e32 v24, -1, v25
	v_and_b32_e32 v24, v25, v24
	v_cndmask_b32_e32 v25, v25, v24, vcc
	v_cmp_lt_u32_e32 vcc, 1, v7
	v_add_u32_e32 v24, -1, v25
	v_and_b32_e32 v24, v25, v24
	v_cndmask_b32_e32 v25, v25, v24, vcc
	v_cmp_lt_u32_e32 vcc, 2, v7
	v_add_u32_e32 v24, -1, v25
	v_and_b32_e32 v24, v25, v24
	v_cndmask_b32_e32 v25, v25, v24, vcc
	v_cmp_lt_u32_e32 vcc, 3, v7
	v_add_u32_e32 v24, -1, v25
	v_and_b32_e32 v24, v25, v24
	v_cndmask_b32_e32 v25, v25, v24, vcc
	v_cmp_lt_u32_e32 vcc, 4, v7
	v_add_u32_e32 v24, -1, v25
	v_and_b32_e32 v24, v25, v24
	v_cndmask_b32_e32 v25, v25, v24, vcc
	v_cmp_lt_u32_e32 vcc, 5, v7
	v_add_u32_e32 v24, -1, v25
	v_and_b32_e32 v24, v25, v24
	v_cndmask_b32_e32 v25, v25, v24, vcc
	v_cmp_lt_u32_e32 vcc, 6, v7
	v_add_u32_e32 v24, -1, v25
	v_and_b32_e32 v24, v25, v24
	v_cndmask_b32_e32 v25, v25, v24, vcc
	v_cmp_lt_u32_e32 vcc, 7, v7
	v_add_u32_e32 v24, -1, v25
	v_and_b32_e32 v24, v25, v24
	v_cndmask_b32_e32 v25, v25, v24, vcc
	v_cmp_lt_u32_e32 vcc, 8, v7
	v_add_u32_e32 v24, -1, v25
	v_and_b32_e32 v24, v25, v24
	v_cndmask_b32_e32 v25, v25, v24, vcc
	v_cmp_lt_u32_e32 vcc, 9, v7
	v_add_u32_e32 v24, -1, v25
	v_and_b32_e32 v24, v25, v24
	v_cndmask_b32_e32 v25, v25, v24, vcc
	v_cmp_lt_u32_e32 vcc, 10, v7
	v_add_u32_e32 v24, -1, v25
	v_and_b32_e32 v24, v25, v24
	v_cndmask_b32_e32 v25, v25, v24, vcc
	v_cmp_lt_u32_e32 vcc, 11, v7
	v_add_u32_e32 v24, -1, v25
	v_and_b32_e32 v24, v25, v24
	v_cndmask_b32_e32 v25, v25, v24, vcc
	v_cmp_lt_u32_e32 vcc, 12, v7
	v_add_u32_e32 v24, -1, v25
	v_and_b32_e32 v24, v25, v24
	v_cndmask_b32_e32 v25, v25, v24, vcc
	v_xor_b32_e32 v25, v33, v25
	v_or_b32_e32 v32, v32, v25

; template <int MODE, bool MASK, bool WITH_O>
; DI void attn_tile_t(lptr Kt, lptr Vt, const bf16x8 (&qf)[4], f32x16& o0, f32x16& o1, RowState& rs, const TP& tp, int lane) {
;     const int hi = lane >> 5;
;     f32x16 s0, s1;
;     bias_init<MODE>(s0, s1, tp, tp.fb - rs.mref, hi);
;     qk_acc(Kt, qf, s0, s1, lane);
;     const float mx = mask_rowmax<MASK>(s0, s1, tp);
;     const bool was = rs.seen; rs.seen = was || (mx > -1e29f);
;     const bool trig = (mx > 8.f) || (!was && mx > -1e29f && mx < -8.f);
;     if (__builtin_expect(__any(trig), 0)) {
; DI void cmpwin_unit(const Params& P, lptr L, int u, int tid, int lane, int wid) {
;     ...
;         ATT_LOOP_BEGIN(NTW, false, kb_ + (size_t)((jw0 + jt) * 64) * PROJ_LD, vb_ + (size_t)(jw0 + jt) * 64, (const float*)nullptr)
;             const int kv0 = (jw0 + jt) * 64;
;             TP tp; tp.cs = nullptr; tp.sl = sl; tp.fb = sl * (float)(kv0 + 8 * hi - t); tp.lim = t - kv0 - 8 * hi; tp.lim2 = tp.lim - 512; tp.sel = true;
;             const bool full = (kv0 + 63 <= tq0) && (tq0 + 31 - kv0 < 512);
;             attn_tile<1>(Kt, Vt, qf, o0, o1, rs, tp, !full, lane);
.LBB0_581:
	s_and_b32 s54, s53, 1
	s_mul_i32 s2, s54, 0x2400
	v_add_u32_e32 v34, s43, v161
	s_add_i32 s55, s2, 0
	s_add_i32 s2, s43, 63
	v_cvt_f32_i32_e32 v34, v34
	s_cmp_gt_u32 s2, s81
	s_cselect_b64 s[2:3], -1, 0
	s_cmp_lt_i32 s43, s23
	s_cselect_b64 s[28:29], -1, 0
	s_or_b64 s[2:3], s[2:3], s[28:29]
	v_mul_f32_e32 v216, v150, v34
	s_andn2_b64 vcc, exec, s[2:3]
	s_mov_b64 s[2:3], -1
	s_cbranch_vccz .LBB0_590
	s_mov_b32 s2, 2.0
	v_sub_f32_e32 v34, v216, v215
	s_mov_b32 s3, 0x40400000
	v_pk_fma_f32 v[84:85], v[166:167], s[2:3], v[34:35] op_sel_hi:[1,1,0]
	s_mov_b32 s2, 4.0
	s_mov_b32 s3, 0x40a00000
	v_pk_fma_f32 v[86:87], v[166:167], s[2:3], v[34:35] op_sel_hi:[1,1,0]
	s_mov_b32 s2, 0x40c00000
	s_mov_b32 s3, 0x40e00000
	v_pk_fma_f32 v[88:89], v[166:167], s[2:3], v[34:35] op_sel_hi:[1,1,0]
	s_mov_b32 s2, 0x41800000
	s_mov_b32 s3, 0x41880000
	v_pk_fma_f32 v[90:91], v[166:167], s[2:3], v[34:35] op_sel_hi:[1,1,0]
	s_mov_b32 s2, 0x41900000
	s_mov_b32 s3, 0x41980000
	v_pk_fma_f32 v[92:93], v[166:167], s[2:3], v[34:35] op_sel_hi:[1,1,0]
	s_mov_b32 s2, 0x41a00000
	s_mov_b32 s3, 0x41a80000
	v_mov_b32_e32 v151, v150
	v_add3_u32 v62, s55, v131, v133
	v_fma_f32 v82, 0, v150, v34
	v_add_f32_e32 v83, v150, v34
	v_pk_fma_f32 v[94:95], v[166:167], s[2:3], v[34:35] op_sel_hi:[1,1,0]
	v_pk_fma_f32 v[96:97], v[166:167], s[18:19], v[34:35] op_sel_hi:[1,1,0]
	v_pk_fma_f32 v[80:81], v[150:151], s[4:5], v[34:35] op_sel_hi:[1,1,0]
	v_pk_fma_f32 v[78:79], v[150:151], s[14:15], v[34:35] op_sel_hi:[1,1,0]
	v_pk_fma_f32 v[76:77], v[150:151], s[16:17], v[34:35] op_sel_hi:[1,1,0]
	v_pk_fma_f32 v[74:75], v[150:151], s[94:95], v[34:35] op_sel_hi:[1,1,0]
	v_pk_fma_f32 v[72:73], v[150:151], s[96:97], v[34:35] op_sel_hi:[1,1,0]
	v_pk_fma_f32 v[70:71], v[150:151], s[84:85], v[34:35] op_sel_hi:[1,1,0]
	v_pk_fma_f32 v[68:69], v[150:151], s[72:73], v[34:35] op_sel_hi:[1,1,0]
	v_pk_fma_f32 v[66:67], v[168:169], s[44:45], v[34:35] op_sel_hi:[1,1,0]
	ds_read_b128 v[34:37], v62 offset:4608
	ds_read_b128 v[38:41], v62
	ds_read_b128 v[42:45], v62 offset:32
	ds_read_b128 v[46:49], v62 offset:4640
	ds_read_b128 v[50:53], v62 offset:64
	ds_read_b128 v[54:57], v62 offset:4672
	ds_read_b128 v[58:61], v62 offset:96
	ds_read_b128 v[62:65], v62 offset:4704
	s_setprio 1
	s_waitcnt lgkmcnt(6)
	v_mfma_f32_32x32x16_bf16 v[82:97], v[38:41], v[98:101], v[82:97]
	v_mfma_f32_32x32x16_bf16 v[66:81], v[34:37], v[98:101], v[66:81]
	s_waitcnt lgkmcnt(5)
	v_mfma_f32_32x32x16_bf16 v[82:97], v[42:45], v[102:105], v[82:97]
	s_waitcnt lgkmcnt(4)
	v_mfma_f32_32x32x16_bf16 v[66:81], v[46:49], v[102:105], v[66:81]
	s_waitcnt lgkmcnt(3)
	v_mfma_f32_32x32x16_bf16 v[82:97], v[50:53], v[106:109], v[82:97]
	s_waitcnt lgkmcnt(2)
	v_mfma_f32_32x32x16_bf16 v[66:81], v[54:57], v[106:109], v[66:81]
	s_waitcnt lgkmcnt(1)
	v_mfma_f32_32x32x16_bf16 v[82:97], v[58:61], v[110:113], v[82:97]
	s_waitcnt lgkmcnt(0)
	v_mfma_f32_32x32x16_bf16 v[66:81], v[62:65], v[110:113], v[66:81]
	s_setprio 0
	s_nop 10
	v_max_f32_e32 v34, v81, v81
	v_max_f32_e32 v35, v97, v97
	v_min_f32_e32 v34, v35, v34
	v_max3_f32 v35, v34, v82, v66
	v_max3_f32 v34, v34, v83, v67
	s_mov_b32 s2, 0xefa18f08
	v_max3_f32 v35, v35, v84, v68
	v_max3_f32 v34, v34, v85, v69
	s_mov_b64 s[30:31], -1
	v_max3_f32 v35, v35, v86, v70
	v_max3_f32 v34, v34, v87, v71
	s_nop 0
	v_max3_f32 v35, v35, v88, v72
	v_max3_f32 v34, v34, v89, v73
	s_nop 0
	v_max3_f32 v35, v35, v90, v74
	v_max3_f32 v34, v34, v91, v75
	s_nop 0
	v_max3_f32 v35, v35, v92, v76
	v_max3_f32 v34, v34, v93, v77
	s_nop 0
	v_max3_f32 v35, v35, v94, v78
	v_max3_f32 v34, v34, v95, v79
	s_nop 0
	v_max3_f32 v35, v35, v96, v80
	v_max3_f32 v34, v34, v97, v81
	s_nop 0
	v_max_f32_e32 v34, v34, v34
	v_max_f32_e32 v35, v35, v35
	v_max_f32_e32 v34, v35, v34
	ds_bpermute_b32 v35, v149, v34
	s_waitcnt lgkmcnt(0)
	v_max_f32_e32 v35, v35, v35
	v_max_f32_e32 v218, v34, v35
	v_cmp_lt_f32_e64 s[28:29], s2, v218
	s_mov_b32 s2, 0x41000000
	v_cmp_nlt_f32_e32 vcc, s2, v218
	s_and_saveexec_b64 s[2:3], vcc
	s_mov_b32 s30, 0xc1000000
	v_cmp_gt_f32_e32 vcc, s30, v218
	s_xor_b64 s[30:31], s[24:25], -1
	s_and_b64 s[30:31], vcc, s[30:31]
	s_and_b64 s[30:31], s[28:29], s[30:31]
	s_orn2_b64 s[30:31], s[30:31], exec
	s_or_b64 exec, exec, s[2:3]
	v_cndmask_b32_e64 v34, 0, 1, s[30:31]
	v_cmp_ne_u32_e32 vcc, 0, v34
	v_mov_b32_e32 v217, v163
	v_mov_b32_e32 v151, v215
	s_cbranch_vccnz .LBB0_595
; template <int MODE, bool MASK, bool WITH_O>
; DI void attn_tile_t(lptr Kt, lptr Vt, const bf16x8 (&qf)[4], f32x16& o0, f32x16& o1, RowState& rs, const TP& tp, int lane) {
;     ...
;     } else {
;         const int i = lane & 31;
;         lptr vp = Vt + i * KPB + hi * 16;
;         float sum = 0.f;
;     ...
;         PV_STEP(s0, 0, 0) PV_STEP(s0, 8, 32) PV_STEP(s1, 0, 64) PV_STEP(s1, 8, 96)
;     ...
;         rs.l += sum;
.LBB0_585:
	v_exp_f32_e32 v82, v82
	v_exp_f32_e32 v83, v83
	v_add3_u32 v226, s55, v135, v133
	v_exp_f32_e32 v84, v84
	ds_read_b128 v[218:221], v226 offset:18432
	ds_read_b128 v[222:225], v226 offset:23040
	v_exp_f32_e32 v85, v85
	v_exp_f32_e32 v86, v86
	v_exp_f32_e32 v87, v87
	v_exp_f32_e32 v88, v88
	v_exp_f32_e32 v89, v89
	v_add_f32_e32 v227, 0, v82
	v_add_f32_e32 v227, v83, v227
	v_add_f32_e32 v227, v84, v227
	v_add_f32_e32 v227, v85, v227
	v_cvt_pk_bf16_f32 v82, v82, v83
	v_cvt_pk_bf16_f32 v83, v84, v85
	v_cvt_pk_bf16_f32 v84, v86, v87
	v_cvt_pk_bf16_f32 v85, v88, v89
	v_add_f32_e32 v227, v86, v227
	v_add_f32_e32 v227, v87, v227
	s_waitcnt lgkmcnt(1)
	v_mfma_f32_32x32x16_bf16 v[18:33], v[218:221], v[82:85], v[18:33]
	v_add_f32_e32 v227, v88, v227
	v_add_f32_e32 v227, v89, v227
	s_waitcnt lgkmcnt(0)
	v_mfma_f32_32x32x16_bf16 v[2:17], v[222:225], v[82:85], v[2:17]
	v_exp_f32_e32 v90, v90
	v_exp_f32_e32 v91, v91
	v_exp_f32_e32 v92, v92
	ds_read_b128 v[82:85], v226 offset:18464
	ds_read_b128 v[86:89], v226 offset:23072
	v_exp_f32_e32 v93, v93
	v_exp_f32_e32 v94, v94
	v_exp_f32_e32 v95, v95
	v_exp_f32_e32 v96, v96
	v_exp_f32_e32 v97, v97
	v_add_f32_e32 v218, v90, v227
	v_add_f32_e32 v218, v91, v218
	v_add_f32_e32 v218, v92, v218
	v_add_f32_e32 v218, v93, v218
	v_cvt_pk_bf16_f32 v90, v90, v91
	v_cvt_pk_bf16_f32 v91, v92, v93
	v_cvt_pk_bf16_f32 v92, v94, v95
	v_cvt_pk_bf16_f32 v93, v96, v97
	v_add_f32_e32 v218, v94, v218
	v_add_f32_e32 v218, v95, v218
	s_waitcnt lgkmcnt(1)
	v_mfma_f32_32x32x16_bf16 v[18:33], v[82:85], v[90:93], v[18:33]
	v_add_f32_e32 v218, v96, v218
	v_add_f32_e32 v218, v97, v218
	s_waitcnt lgkmcnt(0)
	v_mfma_f32_32x32x16_bf16 v[2:17], v[86:89], v[90:93], v[2:17]
	v_exp_f32_e32 v66, v66
	v_exp_f32_e32 v67, v67
	v_exp_f32_e32 v68, v68
	ds_read_b128 v[82:85], v226 offset:18496
	ds_read_b128 v[86:89], v226 offset:23104
	v_exp_f32_e32 v69, v69
	v_exp_f32_e32 v70, v70
	v_exp_f32_e32 v71, v71
	v_exp_f32_e32 v72, v72
	v_exp_f32_e32 v73, v73
	v_add_f32_e32 v90, v66, v218
	v_add_f32_e32 v90, v67, v90
	v_add_f32_e32 v90, v68, v90
	v_add_f32_e32 v90, v69, v90
	v_cvt_pk_bf16_f32 v66, v66, v67
	v_cvt_pk_bf16_f32 v67, v68, v69
	v_cvt_pk_bf16_f32 v68, v70, v71
	v_cvt_pk_bf16_f32 v69, v72, v73
	v_add_f32_e32 v90, v70, v90
	v_add_f32_e32 v90, v71, v90
	s_waitcnt lgkmcnt(1)
	v_mfma_f32_32x32x16_bf16 v[18:33], v[82:85], v[66:69], v[18:33]
	v_add_f32_e32 v90, v72, v90
	v_add_f32_e32 v90, v73, v90
	s_waitcnt lgkmcnt(0)
	v_mfma_f32_32x32x16_bf16 v[2:17], v[86:89], v[66:69], v[2:17]
	v_exp_f32_e32 v67, v74
	v_exp_f32_e32 v72, v75
	v_exp_f32_e32 v73, v76
	v_exp_f32_e32 v74, v77
	ds_read_b128 v[68:71], v226 offset:18528
	ds_read_b128 v[82:85], v226 offset:23136
	v_add_f32_e32 v66, v67, v90
	v_exp_f32_e32 v75, v78
	v_exp_f32_e32 v76, v79
	v_exp_f32_e32 v77, v80
	v_exp_f32_e32 v78, v81
	v_add_f32_e32 v66, v72, v66
	v_add_f32_e32 v66, v73, v66
	v_add_f32_e32 v66, v74, v66
	v_add_f32_e32 v66, v75, v66
	v_cvt_pk_bf16_f32 v72, v67, v72
	v_cvt_pk_bf16_f32 v73, v73, v74
	v_cvt_pk_bf16_f32 v74, v75, v76
	v_cvt_pk_bf16_f32 v75, v77, v78
	v_add_f32_e32 v66, v76, v66
	v_add_f32_e32 v66, v77, v66
	s_waitcnt lgkmcnt(1)
	v_mfma_f32_32x32x16_bf16 v[18:33], v[68:71], v[72:75], v[18:33]
	v_add_f32_e32 v66, v78, v66
	s_waitcnt lgkmcnt(0)
	v_mfma_f32_32x32x16_bf16 v[2:17], v[82:85], v[72:75], v[2:17]

.LBB0_587:
	s_xor_b32 s2, s54, 1
	s_mulk_i32 s2, 0x2400
	v_add_u32_e32 v34, s2, v127
	s_waitcnt vmcnt(1)
	ds_write_b128 v34, v[114:117]
	s_waitcnt vmcnt(0)
	ds_write_b128 v34, v[118:121] offset:18432
.LBB0_588:
	s_add_i32 s53, s53, 1
	s_or_b64 s[24:25], s[24:25], s[28:29]
	s_add_i32 s43, s43, 64
	s_add_i32 s2, s52, s53
	v_add_f32_e32 v163, v217, v66
	s_cmp_lg_u32 s2, 0
	v_subrev_u32_e32 v155, 64, v155
	s_waitcnt lgkmcnt(0)
	s_barrier
	s_cbranch_scc0 .Lwin_exit
	v_mov_b32_e32 v215, v151
	s_cmp_lt_i32 s53, s42
	s_cselect_b64 s[26:27], -1, 0
	s_cmp_ge_i32 s53, s42
	s_cbranch_scc0 .LBB0_580
	s_branch .LBB0_581

; DI float exp2_fast(float x) { return __builtin_amdgcn_exp2f(x); }
; template <int MODE, bool MASK, bool WITH_O>
; DI void attn_tile_t(lptr Kt, lptr Vt, const bf16x8 (&qf)[4], f32x16& o0, f32x16& o1, RowState& rs, const TP& tp, int lane) {
;     ...
;     if (__builtin_expect(__any(trig), 0)) {
;         asm volatile("" ::: "memory");
;         const float d = trig ? mx : 0.f; rs.mref += d;
;         const float al = was ? exp2_fast(-d) : 1.f; rs.l *= al;
;         if (WITH_O) { o0 = o0 * al; o1 = o1 * al; }
; #pragma unroll
;         for (int r = 0; r < 16; ++r) { s0[r] -= d; s1[r] -= d; }
;     }
;     if (!WITH_O) {
;         float sum = 0.f;
; #pragma unroll
;         for (int r = 0; r < 16; ++r) { s0[r] = exp2_fast(s0[r]); s1[r] = exp2_fast(s1[r]); sum += s0[r] + s1[r]; }
;         rs.l += sum;
;     } else {
;         const int i = lane & 31;
;         lptr vp = Vt + i * KPB + hi * 16;
;         float sum = 0.f;
;     ...
;         PV_STEP(s0, 0, 0) PV_STEP(s0, 8, 32) PV_STEP(s1, 0, 64) PV_STEP(s1, 8, 96)
;     ...
;         rs.l += sum;
.LBB0_594:
	v_exp_f32_e32 v48, v75
	v_exp_f32_e32 v68, v68
	v_exp_f32_e32 v72, v72
	v_exp_f32_e32 v69, v69
	v_add_f32_e32 v49, 0, v48
	v_exp_f32_e32 v73, v73
	v_add_f32_e32 v49, v68, v49
	v_exp_f32_e32 v70, v70
	v_add3_u32 v76, s55, v135, v133
	v_add_f32_e32 v49, v72, v49
	v_exp_f32_e32 v74, v74
	ds_read_b128 v[58:61], v76 offset:18432
	ds_read_b128 v[62:65], v76 offset:23040
	v_add_f32_e32 v49, v69, v49
	v_exp_f32_e32 v71, v71
	v_add_f32_e32 v49, v73, v49
	v_add_f32_e32 v49, v70, v49
	v_add_f32_e32 v49, v74, v49
	v_add_f32_e32 v49, v71, v49
	v_cvt_pk_bf16_f32 v68, v48, v68
	v_cvt_pk_bf16_f32 v69, v72, v69
	v_cvt_pk_bf16_f32 v70, v73, v70
	v_cvt_pk_bf16_f32 v71, v74, v71
	s_waitcnt lgkmcnt(1)
	s_nop 0
	v_mfma_f32_32x32x16_bf16 v[18:33], v[58:61], v[68:71], v[18:33]
	s_waitcnt lgkmcnt(0)
	v_mfma_f32_32x32x16_bf16 v[2:17], v[62:65], v[68:71], v[2:17]
	v_exp_f32_e32 v48, v57
	v_exp_f32_e32 v43, v43
	v_exp_f32_e32 v56, v56
	v_exp_f32_e32 v57, v42
	v_add_f32_e32 v49, v48, v49
	v_exp_f32_e32 v46, v46
	v_add_f32_e32 v49, v43, v49
	v_exp_f32_e32 v44, v44
	v_add_f32_e32 v49, v56, v49
	v_exp_f32_e32 v47, v47
	ds_read_b128 v[58:61], v76 offset:18464
	ds_read_b128 v[62:65], v76 offset:23072
	v_add_f32_e32 v42, v57, v49
	v_exp_f32_e32 v45, v45
	v_add_f32_e32 v42, v46, v42
	v_add_f32_e32 v42, v44, v42
	v_add_f32_e32 v42, v47, v42
	v_add_f32_e32 v68, v45, v42
	v_cvt_pk_bf16_f32 v42, v48, v43
	v_cvt_pk_bf16_f32 v43, v56, v57
	v_cvt_pk_bf16_f32 v44, v46, v44
	v_cvt_pk_bf16_f32 v45, v47, v45
	s_waitcnt lgkmcnt(1)
	s_nop 0
	v_mfma_f32_32x32x16_bf16 v[18:33], v[58:61], v[42:45], v[18:33]
	s_waitcnt lgkmcnt(0)
	v_mfma_f32_32x32x16_bf16 v[2:17], v[62:65], v[42:45], v[2:17]
	v_exp_f32_e32 v56, v67
	v_exp_f32_e32 v51, v51
	v_exp_f32_e32 v58, v66
	v_exp_f32_e32 v59, v50
	v_add_f32_e32 v57, v56, v68
	v_exp_f32_e32 v54, v54
	v_add_f32_e32 v57, v51, v57
	v_exp_f32_e32 v52, v52
	v_add_f32_e32 v57, v58, v57
	v_exp_f32_e32 v55, v55
	ds_read_b128 v[42:45], v76 offset:18496
	ds_read_b128 v[46:49], v76 offset:23104
	v_add_f32_e32 v50, v59, v57
	v_exp_f32_e32 v53, v53
	v_add_f32_e32 v50, v54, v50
	v_add_f32_e32 v50, v52, v50
	v_add_f32_e32 v50, v55, v50
	v_add_f32_e32 v57, v53, v50
	v_cvt_pk_bf16_f32 v50, v56, v51
	v_cvt_pk_bf16_f32 v51, v58, v59
	v_cvt_pk_bf16_f32 v52, v54, v52
	v_cvt_pk_bf16_f32 v53, v55, v53
	s_waitcnt lgkmcnt(1)
	s_nop 0
	v_mfma_f32_32x32x16_bf16 v[18:33], v[42:45], v[50:53], v[18:33]
	s_waitcnt lgkmcnt(0)
	v_mfma_f32_32x32x16_bf16 v[2:17], v[46:49], v[50:53], v[2:17]
	v_exp_f32_e32 v41, v41
	v_exp_f32_e32 v35, v35
	v_exp_f32_e32 v38, v38
	v_exp_f32_e32 v51, v34
	v_add_f32_e32 v50, v41, v57
	v_exp_f32_e32 v39, v39
	v_add_f32_e32 v50, v35, v50
	v_exp_f32_e32 v36, v36
	v_add_f32_e32 v50, v38, v50
	v_exp_f32_e32 v40, v40
	ds_read_b128 v[42:45], v76 offset:18528
	ds_read_b128 v[46:49], v76 offset:23136
	v_add_f32_e32 v34, v51, v50
	v_exp_f32_e32 v37, v37
	v_add_f32_e32 v34, v39, v34
	v_add_f32_e32 v34, v36, v34
	v_add_f32_e32 v34, v40, v34
	v_add_f32_e32 v66, v37, v34
	v_cvt_pk_bf16_f32 v34, v41, v35
	v_cvt_pk_bf16_f32 v35, v38, v51
	v_cvt_pk_bf16_f32 v36, v39, v36
	v_cvt_pk_bf16_f32 v37, v40, v37
	s_waitcnt lgkmcnt(1)
	s_nop 0
	v_mfma_f32_32x32x16_bf16 v[18:33], v[42:45], v[34:37], v[18:33]
	s_waitcnt lgkmcnt(0)
	v_mfma_f32_32x32x16_bf16 v[2:17], v[46:49], v[34:37], v[2:17]
	s_nop 11
	v_mov_b32_e32 v151, v215
	v_mov_b32_e32 v217, v163
	s_andn2_b64 vcc, exec, s[26:27]
	s_cbranch_vccz .LBB0_587
	s_branch .LBB0_588
.LBB0_595:
	v_cndmask_b32_e64 v218, 0, v218, s[30:31]
	v_exp_f32_e64 v34, -v218
	v_add_f32_e32 v151, v215, v218
	v_pk_add_f32 v[82:83], v[82:83], v[218:219] op_sel_hi:[1,0] neg_lo:[0,1] neg_hi:[0,1]
	v_cndmask_b32_e64 v34, 1.0, v34, s[24:25]
	v_mul_f32_e32 v217, v163, v34
	v_pk_mul_f32 v[32:33], v[32:33], v[34:35] op_sel_hi:[1,0]
	v_pk_mul_f32 v[30:31], v[30:31], v[34:35] op_sel_hi:[1,0]
	v_pk_mul_f32 v[28:29], v[28:29], v[34:35] op_sel_hi:[1,0]
	v_pk_mul_f32 v[26:27], v[26:27], v[34:35] op_sel_hi:[1,0]
	v_pk_mul_f32 v[24:25], v[24:25], v[34:35] op_sel_hi:[1,0]
	v_pk_mul_f32 v[22:23], v[22:23], v[34:35] op_sel_hi:[1,0]
	v_pk_mul_f32 v[20:21], v[20:21], v[34:35] op_sel_hi:[1,0]
	v_pk_mul_f32 v[18:19], v[18:19], v[34:35] op_sel_hi:[1,0]
	v_pk_mul_f32 v[16:17], v[16:17], v[34:35] op_sel_hi:[1,0]
	v_pk_mul_f32 v[14:15], v[14:15], v[34:35] op_sel_hi:[1,0]
	v_pk_mul_f32 v[12:13], v[12:13], v[34:35] op_sel_hi:[1,0]
	v_pk_mul_f32 v[10:11], v[10:11], v[34:35] op_sel_hi:[1,0]
	v_pk_mul_f32 v[8:9], v[8:9], v[34:35] op_sel_hi:[1,0]
	v_pk_mul_f32 v[6:7], v[6:7], v[34:35] op_sel_hi:[1,0]
	v_pk_mul_f32 v[4:5], v[4:5], v[34:35] op_sel_hi:[1,0]
	v_pk_mul_f32 v[2:3], v[2:3], v[34:35] op_sel_hi:[1,0]
	v_pk_add_f32 v[66:67], v[66:67], v[218:219] op_sel_hi:[1,0] neg_lo:[0,1] neg_hi:[0,1]
	v_pk_add_f32 v[84:85], v[84:85], v[218:219] op_sel_hi:[1,0] neg_lo:[0,1] neg_hi:[0,1]
	v_pk_add_f32 v[68:69], v[68:69], v[218:219] op_sel_hi:[1,0] neg_lo:[0,1] neg_hi:[0,1]
	v_pk_add_f32 v[86:87], v[86:87], v[218:219] op_sel_hi:[1,0] neg_lo:[0,1] neg_hi:[0,1]
	v_pk_add_f32 v[70:71], v[70:71], v[218:219] op_sel_hi:[1,0] neg_lo:[0,1] neg_hi:[0,1]
	v_pk_add_f32 v[88:89], v[88:89], v[218:219] op_sel_hi:[1,0] neg_lo:[0,1] neg_hi:[0,1]
	v_pk_add_f32 v[72:73], v[72:73], v[218:219] op_sel_hi:[1,0] neg_lo:[0,1] neg_hi:[0,1]
	v_pk_add_f32 v[90:91], v[90:91], v[218:219] op_sel_hi:[1,0] neg_lo:[0,1] neg_hi:[0,1]
	v_pk_add_f32 v[74:75], v[74:75], v[218:219] op_sel_hi:[1,0] neg_lo:[0,1] neg_hi:[0,1]
	v_pk_add_f32 v[92:93], v[92:93], v[218:219] op_sel_hi:[1,0] neg_lo:[0,1] neg_hi:[0,1]
	v_pk_add_f32 v[76:77], v[76:77], v[218:219] op_sel_hi:[1,0] neg_lo:[0,1] neg_hi:[0,1]
	v_pk_add_f32 v[94:95], v[94:95], v[218:219] op_sel_hi:[1,0] neg_lo:[0,1] neg_hi:[0,1]
	v_pk_add_f32 v[78:79], v[78:79], v[218:219] op_sel_hi:[1,0] neg_lo:[0,1] neg_hi:[0,1]
	v_pk_add_f32 v[96:97], v[96:97], v[218:219] op_sel_hi:[1,0] neg_lo:[0,1] neg_hi:[0,1]
	v_pk_add_f32 v[80:81], v[80:81], v[218:219] op_sel_hi:[1,0] neg_lo:[0,1] neg_hi:[0,1]
	s_branch .LBB0_585

; #define ATT_LOOP_END(NT, HASCS) } \
;       if (jt_ + 1 < (NT)) { tile_lstore(L + AL_K + (cur_ ^ 1) * TILE_B, L + AL_V + (cur_ ^ 1) * TILE_B, kr_, vr_, tid); if (HASCS && tid < 64) ((LAS float*)(L + AL_CS))[(cur_ ^ 1) * 64 + tid] = csr_; } \
;       __syncthreads(); } }
; DI void cmpwin_unit(const Params& P, lptr L, int u, int tid, int lane, int wid) {
;     ...
;         ATT_LOOP_END(NTW, false)
;         float l = rs.l; l += __shfl_xor(l, 32);
;         const float sc = gwn / fmaxf(l, 1e-30f);
;         float* prow = PART + row * 512 + head * 64;
.Lwin_exit:
	s_nop 3
	v_mov_b64_e32 v[34:35], v[18:19]
	v_mov_b64_e32 v[36:37], v[20:21]
	v_mov_b64_e32 v[38:39], v[22:23]
	v_mov_b64_e32 v[40:41], v[24:25]
	v_mov_b64_e32 v[42:43], v[26:27]
	v_mov_b64_e32 v[44:45], v[28:29]
	v_mov_b64_e32 v[46:47], v[30:31]
	v_mov_b64_e32 v[48:49], v[32:33]
	v_mov_b64_e32 v[50:51], v[2:3]
	v_mov_b64_e32 v[52:53], v[4:5]
	v_mov_b64_e32 v[54:55], v[6:7]
	v_mov_b64_e32 v[56:57], v[8:9]
	v_mov_b64_e32 v[58:59], v[10:11]
	v_mov_b64_e32 v[60:61], v[12:13]
	v_mov_b64_e32 v[62:63], v[14:15]
	v_mov_b64_e32 v[64:65], v[16:17]
	s_branch .LBB0_598

; template <int MODE, bool MASK, bool WITH_O>
; DI void attn_tile_t(lptr Kt, lptr Vt, const bf16x8 (&qf)[4], f32x16& o0, f32x16& o1, RowState& rs, const TP& tp, int lane) {
;     const int hi = lane >> 5;
;     f32x16 s0, s1;
;     bias_init<MODE>(s0, s1, tp, tp.fb - rs.mref, hi);
;     qk_acc(Kt, qf, s0, s1, lane);
;     const float mx = mask_rowmax<MASK>(s0, s1, tp);
; DI void slc_unit(const Params& P, lptr L, int u, int tid, int lane, int wid) {
;     ...
;     ATT_LOOP_BEGIN(NTS, false, kb_ + (size_t)((int)list[jt] * 64) * PROJ_LD, vb_ + (size_t)((int)list[jt]) * 64, (const float*)nullptr)
;         const int j = (int)list[jt], kv0 = j * 64;
;         const bool sel = (sm[ql * 8 + (j >> 5)] >> (j & 31)) & 1u;
;         if (__any(sel)) {
;             TP tp; tp.cs = nullptr; tp.sl = sl; tp.fb = sl * (float)(kv0 + 8 * hi - t); tp.lim = t - kv0 - 8 * hi; tp.lim2 = -(1 << 30); tp.sel = sel;
;             attn_tile<1>(Kt, Vt, qf, o0, o1, rs, tp, true, lane);
;         }
.LBB0_613:
	s_add_i32 s1, s0, 0
	s_add_i32 s1, s1, 0x1a104
	v_mov_b32_e32 v0, s1
	ds_read_u8 v0, v0
	s_and_b32 s31, s0, 1
	s_waitcnt lgkmcnt(0)
	v_lshrrev_b32_e32 v34, 3, v0
	v_and_b32_e32 v34, 28, v34
	v_add_u32_e32 v34, v186, v34
	ds_read_b32 v34, v34
	v_and_b32_e32 v35, 31, v0
	s_waitcnt lgkmcnt(0)
	v_lshrrev_b32_e32 v36, v0, v34
	v_bfe_u32 v34, v34, v35, 1
	v_and_b32_e32 v35, 1, v36
	v_cmp_ne_u32_e32 vcc, 0, v34
	v_cmp_eq_u32_e64 s[28:29], 1, v35
	s_cbranch_vccz .LBB0_618
	v_lshl_or_b32 v0, v0, 6, v126
	v_sub_u32_e32 v34, v0, v91
	v_cvt_f32_i32_e32 v34, v34
	s_mov_b32 s0, 2.0
	v_sub_u32_e32 v152, v91, v0
	s_mov_b32 s1, 0x40400000
	v_cmp_lt_i32_e32 vcc, 54, v152
	v_fma_f32 v0, v150, v34, -v101
	s_cmp_eq_u64 vcc, exec
	s_cselect_b64 s[98:99], -1, 0
	s_orn2_b64 s[100:101], s[28:29], s[98:99]
	v_cndmask_b32_e64 v0, v210, v0, s[100:101]
	v_pk_fma_f32 v[36:37], v[94:95], s[0:1], v[0:1] op_sel_hi:[1,1,0]
	s_mov_b32 s0, 4.0
	s_mov_b32 s1, 0x40a00000
	v_pk_fma_f32 v[38:39], v[94:95], s[0:1], v[0:1] op_sel_hi:[1,1,0]
	s_mov_b32 s0, 0x40c00000
	s_mov_b32 s1, 0x40e00000
	v_pk_fma_f32 v[40:41], v[94:95], s[0:1], v[0:1] op_sel_hi:[1,1,0]
	s_mov_b32 s0, 0x41800000
	s_mov_b32 s1, 0x41880000
	v_pk_fma_f32 v[42:43], v[94:95], s[0:1], v[0:1] op_sel_hi:[1,1,0]
	s_mov_b32 s0, 0x41900000
	s_mov_b32 s1, 0x41980000
	v_pk_fma_f32 v[44:45], v[94:95], s[0:1], v[0:1] op_sel_hi:[1,1,0]
	s_mov_b32 s0, 0x41a00000
	s_mul_i32 s33, s31, 0x2400
	s_mov_b32 s1, 0x41a80000
	v_mov_b32_e32 v151, v150
	v_fma_f32 v34, 0, v150, v0
	v_add_f32_e32 v35, v150, v0
	v_pk_fma_f32 v[46:47], v[94:95], s[0:1], v[0:1] op_sel_hi:[1,1,0]
	v_pk_fma_f32 v[48:49], v[94:95], s[18:19], v[0:1] op_sel_hi:[1,1,0]
	v_pk_fma_f32 v[64:65], v[150:151], s[4:5], v[0:1] op_sel_hi:[1,1,0]
	v_pk_fma_f32 v[62:63], v[150:151], s[14:15], v[0:1] op_sel_hi:[1,1,0]
	v_pk_fma_f32 v[60:61], v[150:151], s[16:17], v[0:1] op_sel_hi:[1,1,0]
	v_pk_fma_f32 v[58:59], v[150:151], s[94:95], v[0:1] op_sel_hi:[1,1,0]
	v_pk_fma_f32 v[56:57], v[150:151], s[96:97], v[0:1] op_sel_hi:[1,1,0]
	v_pk_fma_f32 v[54:55], v[150:151], s[84:85], v[0:1] op_sel_hi:[1,1,0]
	v_pk_fma_f32 v[52:53], v[150:151], s[72:73], v[0:1] op_sel_hi:[1,1,0]
	v_pk_fma_f32 v[50:51], v[96:97], s[44:45], v[0:1] op_sel_hi:[1,1,0]
	v_add_u32_e32 v0, s33, v170
	ds_read_b128 v[102:105], v0 offset:4608
	ds_read_b128 v[106:109], v0
	ds_read_b128 v[110:113], v0 offset:32
	ds_read_b128 v[114:117], v0 offset:4640
	ds_read_b128 v[118:121], v0 offset:64
	ds_read_b128 v[158:161], v0 offset:4672
	ds_read_b128 v[162:165], v0 offset:96
	ds_read_b128 v[166:169], v0 offset:4704
	s_setprio 1
	s_waitcnt lgkmcnt(6)
	v_mfma_f32_32x32x16_bf16 v[34:49], v[106:109], v[66:69], v[34:49]
	v_mfma_f32_32x32x16_bf16 v[50:65], v[102:105], v[66:69], v[50:65]
	s_waitcnt lgkmcnt(5)
	v_mfma_f32_32x32x16_bf16 v[34:49], v[110:113], v[70:73], v[34:49]
	s_waitcnt lgkmcnt(4)
	v_mfma_f32_32x32x16_bf16 v[50:65], v[114:117], v[70:73], v[50:65]
	s_waitcnt lgkmcnt(3)
	v_mfma_f32_32x32x16_bf16 v[34:49], v[118:121], v[74:77], v[34:49]
	s_waitcnt lgkmcnt(2)
	v_mfma_f32_32x32x16_bf16 v[50:65], v[158:161], v[74:77], v[50:65]
	s_waitcnt lgkmcnt(1)
	v_mfma_f32_32x32x16_bf16 v[34:49], v[162:165], v[78:81], v[34:49]
	s_waitcnt lgkmcnt(0)
	v_mfma_f32_32x32x16_bf16 v[50:65], v[166:169], v[78:81], v[50:65]
	s_setprio 0
	s_and_b64 vcc, exec, s[98:99]
	s_cbranch_vccz .Lslc_masked
	s_nop 8
	v_mov_b32_e32 v106, v34
	v_mov_b32_e32 v102, v50
	v_mov_b32_e32 v103, v35
	v_mov_b32_e32 v104, v36
	v_mov_b32_e32 v50, v52
	v_mov_b32_e32 v105, v37
	v_mov_b32_e32 v52, v53
	v_mov_b32_e32 v107, v38
	v_mov_b32_e32 v53, v54
	v_mov_b32_e32 v108, v39
	v_mov_b32_e32 v54, v55
	v_mov_b32_e32 v109, v40
	v_mov_b32_e32 v55, v56
	v_mov_b32_e32 v110, v41
	v_mov_b32_e32 v41, v57
	v_mov_b32_e32 v56, v42
	v_mov_b32_e32 v38, v58
	v_mov_b32_e32 v34, v59
	v_mov_b32_e32 v42, v44
	v_mov_b32_e32 v0, v60
	v_mov_b32_e32 v44, v45
	v_mov_b32_e32 v35, v61
	v_mov_b32_e32 v45, v46
	v_mov_b32_e32 v36, v62
	v_mov_b32_e32 v46, v47
	v_mov_b32_e32 v37, v63
	v_mov_b32_e32 v47, v48
	v_mov_b32_e32 v39, v64
	v_mov_b32_e32 v48, v49
	v_mov_b32_e32 v40, v65
	s_branch .Lslc_join
; DI float max3_asm(float a, float b, float c) { float r; asm("v_max3_f32 %0, %1, %2, %3" : "=v"(r) : "v"(a), "v"(b), "v"(c)); return r; }
; template <bool MASK>
; DI float mask_rowmax(f32x16& s0, f32x16& s1, const TP& tp) {
;     if (MASK) {
; #pragma unroll
;         for (int r = 0; r < 16; ++r) {
;             const int kvc = 16 * (r >> 3) + (r & 7);
;             const bool v0 = tp.sel && (kvc <= tp.lim) && (kvc > tp.lim2), v1 = tp.sel && (kvc + 32 <= tp.lim) && (kvc + 32 > tp.lim2);
;             s0[r] = v0 ? s0[r] : -1e30f; s1[r] = v1 ? s1[r] : -1e30f;
;         }
;     }
;     const float seed = __builtin_fminf(s0[15], s1[15]);
;     float ma = seed, mb = seed;
; #pragma unroll
;     for (int r = 0; r < 16; r += 2) { ma = max3_asm(ma, s0[r], s1[r]); mb = max3_asm(mb, s0[r + 1], s1[r + 1]); }
;     const float mx = fmaxf(ma, mb);
;     return fmaxf(mx, __shfl_xor(mx, 32));
; }
; template <int MODE, bool MASK, bool WITH_O>
; DI void attn_tile_t(lptr Kt, lptr Vt, const bf16x8 (&qf)[4], f32x16& o0, f32x16& o1, RowState& rs, const TP& tp, int lane) {
;     const int hi = lane >> 5;
;     f32x16 s0, s1;
;     bias_init<MODE>(s0, s1, tp, tp.fb - rs.mref, hi);
;     qk_acc(Kt, qf, s0, s1, lane);
;     const float mx = mask_rowmax<MASK>(s0, s1, tp);
;     const bool was = rs.seen; rs.seen = was || (mx > -1e29f);
;     const bool trig = (mx > 8.f) || (!was && mx > -1e29f && mx < -8.f);
;     if (__builtin_expect(__any(trig), 0)) {
.Lslc_masked:
	v_cmp_lt_i32_e32 vcc, -1, v152
	v_cmp_lt_i32_e64 s[0:1], 31, v152
	s_and_b64 vcc, s[28:29], vcc
	s_nop 5
	v_cndmask_b32_e32 v106, v210, v34, vcc
	s_and_b64 vcc, s[28:29], s[0:1]
	v_cndmask_b32_e32 v102, v210, v50, vcc
	v_cmp_lt_i32_e32 vcc, 0, v152
	v_cmp_lt_i32_e64 s[0:1], 32, v152
	s_and_b64 vcc, s[28:29], vcc
	v_cndmask_b32_e32 v103, v210, v35, vcc
	s_and_b64 vcc, s[28:29], s[0:1]
	v_cndmask_b32_e32 v51, v210, v51, vcc
	v_cmp_lt_i32_e32 vcc, 1, v152
	v_cmp_lt_i32_e64 s[0:1], 33, v152
	s_and_b64 vcc, s[28:29], vcc
	v_cndmask_b32_e32 v104, v210, v36, vcc
	s_and_b64 vcc, s[28:29], s[0:1]
	v_cndmask_b32_e32 v50, v210, v52, vcc
	v_cmp_lt_i32_e32 vcc, 2, v152
	v_cmp_lt_i32_e64 s[0:1], 34, v152
	s_and_b64 vcc, s[28:29], vcc
	v_cndmask_b32_e32 v105, v210, v37, vcc
	s_and_b64 vcc, s[28:29], s[0:1]
	v_cndmask_b32_e32 v52, v210, v53, vcc
	v_cmp_lt_i32_e32 vcc, 3, v152
	v_cmp_lt_i32_e64 s[0:1], 35, v152
	s_and_b64 vcc, s[28:29], vcc
	v_cndmask_b32_e32 v107, v210, v38, vcc
	s_and_b64 vcc, s[28:29], s[0:1]
	v_cndmask_b32_e32 v53, v210, v54, vcc
	v_cmp_lt_i32_e32 vcc, 4, v152
	v_cmp_lt_i32_e64 s[0:1], 36, v152
	s_and_b64 vcc, s[28:29], vcc
	v_cndmask_b32_e32 v108, v210, v39, vcc
	s_and_b64 vcc, s[28:29], s[0:1]
	v_cndmask_b32_e32 v54, v210, v55, vcc
	v_cmp_lt_i32_e32 vcc, 5, v152
	v_cmp_lt_i32_e64 s[0:1], 37, v152
	s_and_b64 vcc, s[28:29], vcc
	v_cndmask_b32_e32 v109, v210, v40, vcc
	s_and_b64 vcc, s[28:29], s[0:1]
	v_cndmask_b32_e32 v55, v210, v56, vcc
	v_cmp_lt_i32_e32 vcc, 6, v152
	v_cmp_lt_i32_e64 s[0:1], 38, v152
	s_and_b64 vcc, s[28:29], vcc
	v_cndmask_b32_e32 v110, v210, v41, vcc
	s_and_b64 vcc, s[28:29], s[0:1]
	v_cndmask_b32_e32 v41, v210, v57, vcc
	v_cmp_lt_i32_e32 vcc, 15, v152
	v_cmp_lt_i32_e64 s[0:1], 47, v152
	s_and_b64 vcc, s[28:29], vcc
	v_cndmask_b32_e32 v56, v210, v42, vcc
	s_and_b64 vcc, s[28:29], s[0:1]
	v_cndmask_b32_e32 v38, v210, v58, vcc
	v_cmp_lt_i32_e32 vcc, 16, v152
	v_cmp_lt_i32_e64 s[0:1], 48, v152
	s_and_b64 vcc, s[28:29], vcc
	v_cndmask_b32_e32 v43, v210, v43, vcc
	s_and_b64 vcc, s[28:29], s[0:1]
	v_cndmask_b32_e32 v34, v210, v59, vcc
	v_cmp_lt_i32_e32 vcc, 17, v152
	v_cmp_lt_i32_e64 s[0:1], 49, v152
	s_and_b64 vcc, s[28:29], vcc
	v_cndmask_b32_e32 v42, v210, v44, vcc
	s_and_b64 vcc, s[28:29], s[0:1]
	v_cndmask_b32_e32 v0, v210, v60, vcc
	v_cmp_lt_i32_e32 vcc, 18, v152
	v_cmp_lt_i32_e64 s[0:1], 50, v152
	s_and_b64 vcc, s[28:29], vcc
	v_cndmask_b32_e32 v44, v210, v45, vcc
	s_and_b64 vcc, s[28:29], s[0:1]
	v_cndmask_b32_e32 v35, v210, v61, vcc
	v_cmp_lt_i32_e32 vcc, 19, v152
	v_cmp_lt_i32_e64 s[0:1], 51, v152
	s_and_b64 vcc, s[28:29], vcc
	v_cndmask_b32_e32 v45, v210, v46, vcc
	s_and_b64 vcc, s[28:29], s[0:1]
	v_cndmask_b32_e32 v36, v210, v62, vcc
	v_cmp_lt_i32_e32 vcc, 20, v152
	v_cmp_lt_i32_e64 s[0:1], 52, v152
	s_and_b64 vcc, s[28:29], vcc
	v_cndmask_b32_e32 v46, v210, v47, vcc
	s_and_b64 vcc, s[28:29], s[0:1]
	v_cndmask_b32_e32 v37, v210, v63, vcc
	v_cmp_lt_i32_e32 vcc, 21, v152
	v_cmp_lt_i32_e64 s[0:1], 53, v152
	s_and_b64 vcc, s[28:29], vcc
	v_cndmask_b32_e32 v47, v210, v48, vcc
	s_and_b64 vcc, s[28:29], s[0:1]
	v_cndmask_b32_e32 v39, v210, v64, vcc
	v_cmp_lt_i32_e32 vcc, 22, v152
	v_cmp_lt_i32_e64 s[0:1], 54, v152
	s_and_b64 vcc, s[28:29], vcc
	v_cndmask_b32_e32 v48, v210, v49, vcc
	s_and_b64 vcc, s[28:29], s[0:1]
	v_cndmask_b32_e32 v40, v210, v65, vcc
.Lslc_join:
	v_max_f32_e32 v49, v40, v40
	v_max_f32_e32 v57, v48, v48
	v_min_f32_e32 v49, v57, v49
	v_max3_f32 v57, v49, v106, v102
	v_max3_f32 v49, v49, v103, v51
	s_mov_b32 s0, 0xefa18f08
	v_max3_f32 v57, v57, v104, v50
	v_max3_f32 v49, v49, v105, v52
	s_nop 0
	v_max3_f32 v57, v57, v107, v53
	v_max3_f32 v49, v49, v108, v54
	s_nop 0
	v_max3_f32 v57, v57, v109, v55
	v_max3_f32 v49, v49, v110, v41
	s_nop 0
	v_max3_f32 v57, v57, v56, v38
	v_max3_f32 v49, v49, v43, v34
	s_nop 0
	v_max3_f32 v57, v57, v42, v0
	v_max3_f32 v49, v49, v44, v35
	s_nop 0
	v_max3_f32 v57, v57, v45, v36
	v_max3_f32 v49, v49, v46, v37
	s_nop 0
	v_max3_f32 v57, v57, v47, v39
	v_max3_f32 v49, v49, v48, v40
	s_nop 0
	v_max_f32_e32 v49, v49, v49
	v_max_f32_e32 v57, v57, v57
	v_max_f32_e32 v49, v57, v49
	ds_bpermute_b32 v57, v149, v49
	s_waitcnt lgkmcnt(0)
	v_max_f32_e32 v57, v57, v57
	v_max_f32_e32 v49, v49, v57
	v_cmp_lt_f32_e64 s[28:29], s0, v49
	s_mov_b32 s0, 0x41000000
	v_cmp_nlt_f32_e32 vcc, s0, v49
	s_mov_b64 s[0:1], -1
	s_and_saveexec_b64 s[2:3], vcc
	s_mov_b32 s0, 0xc1000000
	v_cmp_gt_f32_e32 vcc, s0, v49
	s_xor_b64 s[0:1], s[22:23], -1
	s_and_b64 s[0:1], vcc, s[0:1]
	s_and_b64 s[0:1], s[28:29], s[0:1]
	s_orn2_b64 s[0:1], s[0:1], exec
	s_or_b64 exec, exec, s[2:3]
	v_cndmask_b32_e64 v57, 0, 1, s[0:1]
	v_cmp_ne_u32_e32 vcc, 0, v57
	s_cbranch_vccnz .LBB0_622
